# LN passes: compiler's conservative in-row vmcnt waits (assuming rare param-reload loads) removed from the common path; rare path drains; loop-tail drain replaced by counted vmcnt(8); on top of v14
# baseline (speedup 1.0000x reference)
.LBB0_502:
	s_or_b64 exec, exec, s[16:17]
	v_cmp_ge_i32_e32 vcc, v213, v83
	v_lshl_add_u64 v[100:101], v[100:101], 0, s[86:87]
	v_lshl_add_u64 v[84:85], v[84:85], 0, s[78:79]
	s_or_b64 s[14:15], vcc, s[14:15]
	s_waitcnt vmcnt(8)
	v_mov_b64_e32 v[178:179], v[132:133]
	v_mov_b64_e32 v[182:183], v[128:129]
	v_mov_b64_e32 v[186:187], v[124:125]
	v_mov_b64_e32 v[190:191], v[120:121]
	v_mov_b64_e32 v[176:177], v[134:135]
	v_mov_b64_e32 v[180:181], v[130:131]
	v_mov_b64_e32 v[184:185], v[126:127]
	v_mov_b64_e32 v[188:189], v[122:123]
	v_mov_b64_e32 v[160:161], v[154:155]
	v_mov_b64_e32 v[164:165], v[150:151]
	v_mov_b64_e32 v[168:169], v[140:141]
	v_mov_b64_e32 v[172:173], v[136:137]
	v_mov_b64_e32 v[158:159], v[156:157]
	v_mov_b64_e32 v[162:163], v[152:153]
	v_mov_b64_e32 v[166:167], v[148:149]
	v_mov_b64_e32 v[170:171], v[138:139]
	v_mov_b32_e32 v174, v213
	s_andn2_b64 exec, exec, s[14:15]
	s_cbranch_execz .LBB0_552

.LBB0_556:
	s_or_b64 exec, exec, s[12:13]
	v_lshlrev_b32_e32 v186, 16, v152
	v_and_b32_e32 v187, 0xffff0000, v152
	v_lshlrev_b32_e32 v152, 16, v153
	v_and_b32_e32 v153, 0xffff0000, v153
	v_lshlrev_b32_e32 v190, 16, v148
	v_and_b32_e32 v191, 0xffff0000, v148
	v_lshlrev_b32_e32 v184, 16, v154
	v_and_b32_e32 v185, 0xffff0000, v154
	v_lshlrev_b32_e32 v154, 16, v155
	v_and_b32_e32 v155, 0xffff0000, v155
	v_lshlrev_b32_e32 v188, 16, v150
	v_and_b32_e32 v189, 0xffff0000, v150
	v_pk_mul_f32 v[190:191], v[54:55], v[190:191]
	v_lshlrev_b32_e32 v148, 16, v149
	v_and_b32_e32 v149, 0xffff0000, v149
	v_pk_mul_f32 v[152:153], v[44:45], v[152:153]
	v_pk_fma_f32 v[188:189], v[188:189], s[14:15], v[190:191] op_sel_hi:[1,0,1]
	v_lshlrev_b32_e32 v150, 16, v151
	v_and_b32_e32 v151, 0xffff0000, v151
	v_pk_mul_f32 v[148:149], v[56:57], v[148:149]
	v_pk_fma_f32 v[152:153], v[154:155], s[14:15], v[152:153] op_sel_hi:[1,0,1]
	v_pk_mul_f32 v[154:155], v[42:43], v[186:187]
	v_pk_fma_f32 v[148:149], v[150:151], s[14:15], v[148:149] op_sel_hi:[1,0,1]
	v_add_f32_e32 v99, v189, v188
	v_pk_fma_f32 v[154:155], v[184:185], s[14:15], v[154:155] op_sel_hi:[1,0,1]
	v_add_f32_e32 v150, v148, v99
	v_add_f32_e32 v99, v155, v154
	v_add_f32_e32 v99, v152, v99
	v_add_f32_e32 v99, v153, v99
	v_add_f32_e32 v185, 0, v99
	v_lshlrev_b32_e32 v99, 16, v136
	v_and_b32_e32 v206, 0xffff0000, v134
	v_lshlrev_b32_e32 v207, 16, v139
	v_pk_mov_b32 v[208:209], v[58:59], v[64:65] op_sel:[1,0]
	v_lshlrev_b32_e32 v192, 16, v138
	v_and_b32_e32 v193, 0xffff0000, v138
	v_mul_f32_e32 v138, 0x3fd744fd, v99
	v_lshlrev_b32_e32 v99, 16, v134
	v_and_b32_e32 v186, 0xffff0000, v136
	v_lshlrev_b32_e32 v187, 16, v141
	v_pk_mul_f32 v[206:207], v[208:209], v[206:207]
	v_lshlrev_b32_e32 v190, 16, v140
	v_and_b32_e32 v191, 0xffff0000, v140
	v_mul_f32_e32 v140, v58, v99
	v_pk_fma_f32 v[186:187], v[186:187], s[14:15], v[206:207] op_sel_hi:[1,0,1]
	v_lshlrev_b32_e32 v206, 16, v137
	v_and_b32_e32 v99, 0xffff0000, v137
	v_pk_mul_f32 v[136:137], v[62:63], v[192:193]
	v_and_b32_e32 v207, 0xffff0000, v141
	v_pk_fma_f32 v[136:137], v[190:191], s[14:15], v[136:137] op_sel_hi:[1,0,1]
	v_lshlrev_b32_e32 v208, 16, v135
	v_and_b32_e32 v209, 0xffff0000, v139
	v_mov_b32_e32 v210, v60
	v_mov_b32_e32 v211, v65
	v_mov_b32_e32 v139, v137
	v_mov_b32_e32 v141, v136
	v_pk_add_f32 v[150:151], v[148:149], v[150:151] op_sel_hi:[1,0]
	v_pk_mul_f32 v[208:209], v[210:211], v[208:209]
	v_mul_f32_e32 v184, 0x3fd744fd, v99
	v_and_b32_e32 v99, 0xffff0000, v135
	v_pk_add_f32 v[138:139], v[138:139], v[140:141]
	v_pk_fma_f32 v[206:207], v[206:207], s[14:15], v[208:209] op_sel_hi:[1,0,1]
	v_mul_f32_e32 v150, v61, v99
	v_pk_add_f32 v[140:141], v[186:187], v[138:139]
	v_pk_add_f32 v[134:135], v[184:185], v[150:151]
	v_pk_add_f32 v[140:141], v[206:207], v[140:141]
	v_mov_b32_e32 v139, v186
	v_pk_add_f32 v[140:141], v[140:141], v[134:135]
	v_ashrrev_i32_e32 v171, 31, v170
	v_add_f32_e32 v99, v140, v141
	v_mov_b32_e32 v140, v187
	v_mov_b32_e32 v141, v207
	v_mov_b32_e32 v207, v134
	s_waitcnt lgkmcnt(0)
	v_mov_b32_e32 v101, v99
	s_nop 1
	v_permlane32_swap_b32_e32 v99, v101
	v_add_f32_e32 v99, v99, v101
	v_mov_b32_e32 v101, v99
	s_nop 1
	v_permlane16_swap_b32_e32 v99, v101
	v_add_f32_e32 v99, v99, v101
	s_nop 1
	v_add_f32_dpp v99, v99, v99 row_ror:8 row_mask:0xf bank_mask:0xf
	s_nop 1
	v_add_f32_dpp v99, v99, v99 row_half_mirror row_mask:0xf bank_mask:0xf
	s_nop 1
	v_add_f32_dpp v99, v99, v99 quad_perm:[2,3,0,1] row_mask:0xf bank_mask:0xf
	s_nop 1
	v_add_f32_dpp v99, v99, v99 quad_perm:[1,0,3,2] row_mask:0xf bank_mask:0xf
	v_mul_f32_e32 v150, 0x3a800000, v99
	v_pk_add_f32 v[154:155], v[154:155], v[150:151] op_sel_hi:[1,0] neg_lo:[0,1] neg_hi:[0,1]
	v_pk_add_f32 v[152:153], v[152:153], v[150:151] op_sel_hi:[1,0] neg_lo:[0,1] neg_hi:[0,1]
	v_pk_mul_f32 v[184:185], v[154:155], v[154:155]
	v_pk_mul_f32 v[190:191], v[152:153], v[152:153]
	v_add_f32_e32 v99, v184, v185
	v_pk_add_f32 v[188:189], v[188:189], v[150:151] op_sel_hi:[1,0] neg_lo:[0,1] neg_hi:[0,1]
	v_add_f32_e32 v99, v190, v99
	v_pk_mul_f32 v[210:211], v[188:189], v[188:189]
	v_add_f32_e32 v99, v191, v99
	v_pk_add_f32 v[148:149], v[148:149], v[150:151] op_sel_hi:[1,0] neg_lo:[0,1] neg_hi:[0,1]
	v_add_f32_e32 v99, v210, v99
	v_pk_mul_f32 v[208:209], v[148:149], v[148:149]
	v_add_f32_e32 v99, v211, v99
	v_pk_add_f32 v[136:137], v[136:137], v[150:151] op_sel_hi:[1,0] neg_lo:[0,1] neg_hi:[0,1]
	v_add_f32_e32 v99, v208, v99
	v_pk_mul_f32 v[192:193], v[136:137], v[136:137]
	v_add_f32_e32 v99, v209, v99
	v_pk_add_f32 v[140:141], v[140:141], v[150:151] op_sel_hi:[1,0] neg_lo:[0,1] neg_hi:[0,1]
	v_add_f32_e32 v99, v192, v99
	v_pk_mul_f32 v[212:213], v[140:141], v[140:141]
	v_add_f32_e32 v99, v193, v99
	v_pk_add_f32 v[138:139], v[138:139], v[150:151] op_sel_hi:[1,0] neg_lo:[0,1] neg_hi:[0,1]
	v_add_f32_e32 v99, v212, v99
	v_pk_add_f32 v[134:135], v[206:207], v[150:151] op_sel_hi:[1,0] neg_lo:[0,1] neg_hi:[0,1]
	v_pk_mul_f32 v[150:151], v[138:139], v[138:139]
	v_add_f32_e32 v99, v213, v99
	v_add_f32_e32 v99, v150, v99
	v_pk_mul_f32 v[206:207], v[134:135], v[134:135]
	v_add_f32_e32 v99, v151, v99
	v_add_f32_e32 v99, v206, v99
	v_add_f32_e32 v99, v207, v99
	v_lshlrev_b64 v[150:151], 12, v[170:171]
	v_lshlrev_b64 v[170:171], 11, v[170:171]
	v_lshl_add_u64 v[184:185], v[88:89], 0, v[170:171]
	v_lshl_add_u64 v[170:171], s[46:47], 0, v[170:171]
	v_lshl_add_u64 v[150:151], v[90:91], 0, v[150:151]
	v_lshl_add_u64 v[186:187], v[170:171], 0, v[0:1]
	s_waitcnt lgkmcnt(0)
	v_mov_b32_e32 v101, v99
	s_nop 1
	v_permlane32_swap_b32_e32 v99, v101
	v_add_f32_e32 v99, v99, v101
	v_mov_b32_e32 v101, v99
	s_nop 1
	v_permlane16_swap_b32_e32 v99, v101
	v_add_f32_e32 v99, v99, v101
	s_nop 1
	v_add_f32_dpp v99, v99, v99 row_ror:8 row_mask:0xf bank_mask:0xf
	s_nop 1
	v_add_f32_dpp v99, v99, v99 row_half_mirror row_mask:0xf bank_mask:0xf
	s_nop 1
	v_add_f32_dpp v99, v99, v99 quad_perm:[2,3,0,1] row_mask:0xf bank_mask:0xf
	s_nop 1
	v_add_f32_dpp v99, v99, v99 quad_perm:[1,0,3,2] row_mask:0xf bank_mask:0xf
	v_fmamk_f32 v99, v99, 0x3a800000, v146
	v_mul_f32_e32 v101, 0x4b800000, v99
	v_cmp_gt_f32_e32 vcc, s54, v99
	s_nop 1
	v_cndmask_b32_e32 v99, v99, v101, vcc
	v_rsq_f32_e32 v101, v99
	v_mov_b32_e32 v99, v1
	v_lshl_add_u64 v[190:191], v[170:171], 0, v[98:99]
	v_mul_f32_e32 v99, 0x45800000, v101
	v_cndmask_b32_e32 v156, v101, v99, vcc
	v_pk_mul_f32 v[154:155], v[154:155], v[156:157] op_sel_hi:[1,0]
	v_pk_mul_f32 v[152:153], v[152:153], v[156:157] op_sel_hi:[1,0]
	v_pk_fma_f32 v[154:155], v[2:3], v[154:155], v[10:11]
	v_pk_fma_f32 v[152:153], v[4:5], v[152:153], v[12:13]
	v_cvt_pk_bf16_f32 v192, v154, v155
	v_cvt_pk_bf16_f32 v193, v152, v153
	v_pk_fma_f32 v[154:155], v[168:169], v[154:155], v[34:35]
	v_pk_fma_f32 v[152:153], v[166:167], v[152:153], v[36:37]
	v_cvt_pk_bf16_f32 v154, v154, v155
	v_cvt_pk_bf16_f32 v155, v152, v153
	v_pk_mul_f32 v[152:153], v[188:189], v[156:157] op_sel_hi:[1,0]
	v_pk_mul_f32 v[148:149], v[148:149], v[156:157] op_sel_hi:[1,0]
	v_pk_fma_f32 v[152:153], v[6:7], v[152:153], v[14:15]
	v_pk_fma_f32 v[148:149], v[8:9], v[148:149], v[16:17]
	v_pk_mul_f32 v[136:137], v[136:137], v[156:157] op_sel_hi:[1,0]
	v_pk_mul_f32 v[140:141], v[140:141], v[156:157] op_sel_hi:[1,0]
	global_store_dwordx2 v[150:151], v[192:193], off nt
	global_store_dwordx2 v[184:185], v[154:155], off
	v_cvt_pk_bf16_f32 v154, v152, v153
	v_cvt_pk_bf16_f32 v155, v148, v149
	v_pk_fma_f32 v[152:153], v[162:163], v[152:153], v[38:39]
	v_pk_fma_f32 v[148:149], v[164:165], v[148:149], v[40:41]
	v_pk_fma_f32 v[136:137], v[18:19], v[136:137], v[26:27]
	v_pk_fma_f32 v[140:141], v[20:21], v[140:141], v[28:29]
	v_cvt_pk_bf16_f32 v152, v152, v153
	v_cvt_pk_bf16_f32 v153, v148, v149
	v_cvt_pk_bf16_f32 v148, v136, v137
	v_cvt_pk_bf16_f32 v149, v140, v141
	v_pk_fma_f32 v[136:137], v[160:161], v[136:137], v[70:71]
	v_pk_fma_f32 v[140:141], v[158:159], v[140:141], v[72:73]
	v_cvt_pk_bf16_f32 v136, v136, v137
	v_cvt_pk_bf16_f32 v137, v140, v141
	global_store_dwordx2 v[150:151], v[154:155], off offset:512 nt
	global_store_dwordx2 v[186:187], v[152:153], off
	global_store_dwordx2 v[150:151], v[148:149], off offset:1024 nt
	global_store_dwordx2 v[190:191], v[136:137], off
	v_pk_mul_f32 v[136:137], v[138:139], v[156:157] op_sel_hi:[1,0]
	v_pk_mul_f32 v[134:135], v[134:135], v[156:157] op_sel_hi:[1,0]
	v_pk_fma_f32 v[136:137], v[22:23], v[136:137], v[30:31]
	v_pk_fma_f32 v[134:135], v[24:25], v[134:135], v[32:33]
	v_cvt_pk_bf16_f32 v138, v136, v137
	v_cvt_pk_bf16_f32 v139, v134, v135
	v_pk_fma_f32 v[136:137], v[172:173], v[136:137], v[74:75]
	v_pk_fma_f32 v[134:135], v[174:175], v[134:135], v[76:77]
	v_mov_b32_e32 v101, v1
	v_cvt_pk_bf16_f32 v136, v136, v137
	v_cvt_pk_bf16_f32 v137, v134, v135
	v_lshl_add_u64 v[134:135], v[170:171], 0, v[100:101]
	global_store_dwordx2 v[150:151], v[138:139], off offset:1536 nt
	global_store_dwordx2 v[134:135], v[136:137], off
.LBB0_557:
	s_or_b64 exec, exec, s[10:11]
	s_waitcnt vmcnt(8)
	v_cmp_ge_i32_e32 vcc, v182, v83
	v_lshl_add_u64 v[86:87], v[86:87], 0, s[78:79]
	v_lshl_add_u64 v[84:85], v[84:85], 0, s[86:87]
	s_or_b64 s[4:5], vcc, s[4:5]
	v_mov_b64_e32 v[168:169], v[120:121]
	v_mov_b64_e32 v[172:173], v[118:119]
	v_mov_b64_e32 v[166:167], v[124:125]
	v_mov_b64_e32 v[170:171], v[122:123]
	v_mov_b64_e32 v[150:151], v[128:129]
	v_mov_b64_e32 v[154:155], v[126:127]
	v_mov_b64_e32 v[148:149], v[132:133]
	v_mov_b64_e32 v[152:153], v[130:131]
	v_mov_b32_e32 v156, v182
	v_mov_b64_e32 v[136:137], v[114:115]
	v_mov_b64_e32 v[140:141], v[110:111]
	v_mov_b64_e32 v[134:135], v[116:117]
	v_mov_b64_e32 v[138:139], v[112:113]
	v_mov_b64_e32 v[160:161], v[106:107]
	v_mov_b64_e32 v[164:165], v[102:103]
	v_mov_b64_e32 v[158:159], v[108:109]
	v_mov_b64_e32 v[162:163], v[104:105]
	s_andn2_b64 exec, exec, s[4:5]
	s_cbranch_execz .LBB0_563
.LBB0_558:
	v_add_u32_e32 v182, 2, v156
	v_add_u32_e32 v99, 3, v156
	v_min_i32_e32 v102, v182, v176
	v_min_i32_e32 v110, v99, v176
	v_ashrrev_i32_e32 v103, 31, v102
	v_ashrrev_i32_e32 v111, 31, v110
	v_lshlrev_b64 v[104:105], 12, v[102:103]
	v_lshlrev_b64 v[102:103], 11, v[102:103]
	v_lshlrev_b64 v[112:113], 12, v[110:111]
	v_lshlrev_b64 v[110:111], 11, v[110:111]
	v_lshl_add_u64 v[104:105], v[90:91], 0, v[104:105]
	v_lshl_add_u64 v[108:109], v[92:93], 0, v[102:103]
	v_lshl_add_u64 v[112:113], v[90:91], 0, v[112:113]
	v_lshl_add_u64 v[116:117], v[92:93], 0, v[110:111]
	global_load_dwordx2 v[118:119], v[104:105], off nt
	global_load_dwordx2 v[120:121], v[104:105], off offset:512 nt
	global_load_dwordx2 v[102:103], v[104:105], off offset:1024 nt
	global_load_dwordx2 v[106:107], v[104:105], off offset:1536 nt
	global_load_dwordx2 v[122:123], v[108:109], off nt
	global_load_dwordx2 v[124:125], v[108:109], off offset:512 nt
	s_nop 0
	global_load_dwordx2 v[104:105], v[108:109], off offset:1024 nt
	s_nop 0
	global_load_dwordx2 v[108:109], v[108:109], off offset:1536 nt
	s_nop 0
	global_load_dwordx2 v[126:127], v[112:113], off nt
	global_load_dwordx2 v[128:129], v[112:113], off offset:512 nt
	global_load_dwordx2 v[110:111], v[112:113], off offset:1024 nt
	global_load_dwordx2 v[114:115], v[112:113], off offset:1536 nt
	global_load_dwordx2 v[130:131], v[116:117], off nt
	global_load_dwordx2 v[132:133], v[116:117], off offset:512 nt
	s_nop 0
	global_load_dwordx2 v[112:113], v[116:117], off offset:1024 nt
	s_nop 0
	global_load_dwordx2 v[116:117], v[116:117], off offset:1536 nt
	v_add_u32_e32 v99, 0xffffe000, v156
	v_lshrrev_b32_e32 v99, 12, v99
	v_add_u32_e32 v99, 1, v99
	v_cmp_lt_i32_e32 vcc, s55, v156
	s_nop 1
	v_cndmask_b32_e32 v99, 0, v99, vcc
	v_cmp_ne_u32_e32 vcc, v99, v183
	s_and_saveexec_b64 s[10:11], vcc
	s_cbranch_execz .LBB0_560
	v_mul_hi_u32_u24_e32 v35, 0x1800, v99
	v_mul_u32_u24_e32 v34, 0x1800, v99
	v_lshlrev_b64 v[34:35], 2, v[34:35]
	v_lshl_add_u64 v[58:59], v[94:95], 0, v[34:35]
	v_lshl_add_u64 v[34:35], s[6:7], 0, v[34:35]
	v_lshlrev_b32_e32 v36, 2, v82
	v_mov_b32_e32 v37, v1
	v_lshl_add_u64 v[66:67], v[34:35], 0, v[36:37]
	s_movk_i32 s2, 0x1000
	v_add_co_u32_e32 v78, vcc, s2, v66
	v_mov_b32_e32 v183, v99
	s_nop 0
	v_addc_co_u32_e32 v79, vcc, 0, v67, vcc
	global_load_dwordx4 v[34:37], v[66:67], off
	global_load_dwordx4 v[38:41], v[66:67], off offset:1024
	global_load_dwordx4 v[46:49], v[78:79], off
	global_load_dwordx4 v[50:53], v[78:79], off offset:1024
	global_load_dwordx4 v[42:45], v[58:59], off
	global_load_dwordx4 v[54:57], v[58:59], off offset:1024
	global_load_dwordx4 v[62:65], v[58:59], off offset:2048
	s_nop 0
	global_load_dwordx4 v[58:61], v[58:59], off offset:3072
	s_nop 0
	global_load_dwordx4 v[70:73], v[66:67], off offset:2048
	global_load_dwordx4 v[74:77], v[66:67], off offset:3072
	s_nop 0
	global_load_dwordx4 v[66:69], v[78:79], off offset:2048
	s_nop 0
	global_load_dwordx4 v[78:81], v[78:79], off offset:3072
	s_waitcnt vmcnt(0)
.LBB0_560:
	s_or_b64 exec, exec, s[10:11]
	v_lshlrev_b32_e32 v184, 16, v170
	v_and_b32_e32 v185, 0xffff0000, v170
	v_lshlrev_b32_e32 v170, 16, v171
	v_and_b32_e32 v171, 0xffff0000, v171
	v_lshlrev_b32_e32 v188, 16, v166
	v_and_b32_e32 v189, 0xffff0000, v166
	v_lshlrev_b32_e32 v174, 16, v172
	v_and_b32_e32 v175, 0xffff0000, v172
	v_lshlrev_b32_e32 v172, 16, v173
	v_and_b32_e32 v173, 0xffff0000, v173
	v_lshlrev_b32_e32 v186, 16, v168
	v_and_b32_e32 v187, 0xffff0000, v168
	v_pk_mul_f32 v[188:189], v[54:55], v[188:189]
	v_lshlrev_b32_e32 v166, 16, v167
	v_and_b32_e32 v167, 0xffff0000, v167
	v_pk_mul_f32 v[170:171], v[44:45], v[170:171]
	v_pk_fma_f32 v[186:187], v[186:187], s[14:15], v[188:189] op_sel_hi:[1,0,1]
	v_lshlrev_b32_e32 v168, 16, v169
	v_and_b32_e32 v169, 0xffff0000, v169
	v_pk_mul_f32 v[166:167], v[56:57], v[166:167]
	v_pk_fma_f32 v[170:171], v[172:173], s[14:15], v[170:171] op_sel_hi:[1,0,1]
	v_pk_mul_f32 v[172:173], v[42:43], v[184:185]
	v_pk_fma_f32 v[166:167], v[168:169], s[14:15], v[166:167] op_sel_hi:[1,0,1]
	v_add_f32_e32 v99, v187, v186
	v_pk_fma_f32 v[172:173], v[174:175], s[14:15], v[172:173] op_sel_hi:[1,0,1]
	v_add_f32_e32 v168, v166, v99
	v_add_f32_e32 v99, v173, v172
	v_add_f32_e32 v99, v170, v99
	v_add_f32_e32 v99, v171, v99
	v_add_f32_e32 v175, 0, v99
	v_lshlrev_b32_e32 v99, 16, v160
	v_and_b32_e32 v192, 0xffff0000, v158
	v_lshlrev_b32_e32 v193, 16, v163
	v_pk_mov_b32 v[206:207], v[58:59], v[64:65] op_sel:[1,0]
	v_lshlrev_b32_e32 v190, 16, v162
	v_and_b32_e32 v191, 0xffff0000, v162
	v_mul_f32_e32 v162, 0x3fd744fd, v99
	v_lshlrev_b32_e32 v99, 16, v158
	v_and_b32_e32 v184, 0xffff0000, v160
	v_lshlrev_b32_e32 v185, 16, v165
	v_pk_mul_f32 v[192:193], v[206:207], v[192:193]
	v_lshlrev_b32_e32 v188, 16, v164
	v_and_b32_e32 v189, 0xffff0000, v164
	v_mul_f32_e32 v164, v58, v99
	v_pk_fma_f32 v[184:185], v[184:185], s[14:15], v[192:193] op_sel_hi:[1,0,1]
	v_lshlrev_b32_e32 v192, 16, v161
	v_and_b32_e32 v99, 0xffff0000, v161
	v_pk_mul_f32 v[160:161], v[62:63], v[190:191]
	v_and_b32_e32 v193, 0xffff0000, v165
	v_pk_fma_f32 v[160:161], v[188:189], s[14:15], v[160:161] op_sel_hi:[1,0,1]
	v_lshlrev_b32_e32 v206, 16, v159
	v_and_b32_e32 v207, 0xffff0000, v163
	v_mov_b32_e32 v208, v60
	v_mov_b32_e32 v209, v65
	v_mov_b32_e32 v163, v161
	v_mov_b32_e32 v165, v160
	v_pk_add_f32 v[168:169], v[166:167], v[168:169] op_sel_hi:[1,0]
	v_pk_mul_f32 v[206:207], v[208:209], v[206:207]
	v_mul_f32_e32 v174, 0x3fd744fd, v99
	v_and_b32_e32 v99, 0xffff0000, v159
	v_pk_add_f32 v[162:163], v[162:163], v[164:165]
	v_pk_fma_f32 v[192:193], v[192:193], s[14:15], v[206:207] op_sel_hi:[1,0,1]
	v_mul_f32_e32 v168, v61, v99
	v_pk_add_f32 v[164:165], v[184:185], v[162:163]
	v_pk_add_f32 v[158:159], v[174:175], v[168:169]
	v_pk_add_f32 v[164:165], v[192:193], v[164:165]
	v_mov_b32_e32 v163, v184
	v_pk_add_f32 v[164:165], v[164:165], v[158:159]
	s_brev_b32 s2, 40
	v_add_f32_e32 v99, v164, v165
	v_mov_b32_e32 v164, v185
	v_mov_b32_e32 v165, v193
	v_mov_b32_e32 v193, v158
	s_waitcnt lgkmcnt(0)
	v_mov_b32_e32 v101, v99
	s_nop 1
	v_permlane32_swap_b32_e32 v99, v101
	v_add_f32_e32 v99, v99, v101
	v_mov_b32_e32 v101, v99
	s_nop 1
	v_permlane16_swap_b32_e32 v99, v101
	v_add_f32_e32 v99, v99, v101
	s_nop 1
	v_add_f32_dpp v99, v99, v99 row_ror:8 row_mask:0xf bank_mask:0xf
	s_nop 1
	v_add_f32_dpp v99, v99, v99 row_half_mirror row_mask:0xf bank_mask:0xf
	s_nop 1
	v_add_f32_dpp v99, v99, v99 quad_perm:[2,3,0,1] row_mask:0xf bank_mask:0xf
	s_nop 1
	v_add_f32_dpp v99, v99, v99 quad_perm:[1,0,3,2] row_mask:0xf bank_mask:0xf
	v_mul_f32_e32 v168, 0x3a800000, v99
	v_pk_add_f32 v[172:173], v[172:173], v[168:169] op_sel_hi:[1,0] neg_lo:[0,1] neg_hi:[0,1]
	v_pk_add_f32 v[170:171], v[170:171], v[168:169] op_sel_hi:[1,0] neg_lo:[0,1] neg_hi:[0,1]
	v_pk_mul_f32 v[174:175], v[172:173], v[172:173]
	v_pk_mul_f32 v[188:189], v[170:171], v[170:171]
	v_add_f32_e32 v99, v174, v175
	v_pk_add_f32 v[186:187], v[186:187], v[168:169] op_sel_hi:[1,0] neg_lo:[0,1] neg_hi:[0,1]
	v_add_f32_e32 v99, v188, v99
	v_pk_mul_f32 v[208:209], v[186:187], v[186:187]
	v_add_f32_e32 v99, v189, v99
	v_pk_add_f32 v[206:207], v[166:167], v[168:169] op_sel_hi:[1,0] neg_lo:[0,1] neg_hi:[0,1]
	v_add_f32_e32 v99, v208, v99
	v_pk_mul_f32 v[166:167], v[206:207], v[206:207]
	v_add_f32_e32 v99, v209, v99
	v_pk_add_f32 v[190:191], v[160:161], v[168:169] op_sel_hi:[1,0] neg_lo:[0,1] neg_hi:[0,1]
	v_add_f32_e32 v99, v166, v99
	v_pk_mul_f32 v[160:161], v[190:191], v[190:191]
	v_add_f32_e32 v99, v167, v99
	v_pk_add_f32 v[210:211], v[164:165], v[168:169] op_sel_hi:[1,0] neg_lo:[0,1] neg_hi:[0,1]
	v_add_f32_e32 v99, v160, v99
	v_pk_mul_f32 v[164:165], v[210:211], v[210:211]
	v_add_f32_e32 v99, v161, v99
	v_pk_add_f32 v[184:185], v[162:163], v[168:169] op_sel_hi:[1,0] neg_lo:[0,1] neg_hi:[0,1]
	v_add_f32_e32 v99, v164, v99
	v_pk_mul_f32 v[162:163], v[184:185], v[184:185]
	v_add_f32_e32 v99, v165, v99
	v_pk_add_f32 v[192:193], v[192:193], v[168:169] op_sel_hi:[1,0] neg_lo:[0,1] neg_hi:[0,1]
	v_add_f32_e32 v99, v162, v99
	v_pk_mul_f32 v[158:159], v[192:193], v[192:193]
	v_add_f32_e32 v99, v163, v99
	v_add_f32_e32 v99, v158, v99
	v_add_f32_e32 v99, v159, v99
	v_pk_add_f32 v[168:169], v[46:47], 1.0 op_sel_hi:[1,0]
	v_pk_add_f32 v[166:167], v[48:49], 1.0 op_sel_hi:[1,0]
	v_lshl_add_u64 v[188:189], v[84:85], 0, v[96:97]
	v_lshl_add_u64 v[174:175], v[86:87], 0, v[96:97]
	v_pk_add_f32 v[162:163], v[50:51], 1.0 op_sel_hi:[1,0]
	v_pk_add_f32 v[164:165], v[52:53], 1.0 op_sel_hi:[1,0]
	v_pk_add_f32 v[160:161], v[66:67], 1.0 op_sel_hi:[1,0]
	v_pk_add_f32 v[158:159], v[68:69], 1.0 op_sel_hi:[1,0]
	s_waitcnt lgkmcnt(0)
	v_mov_b32_e32 v101, v99
	s_nop 1
	v_permlane32_swap_b32_e32 v99, v101
	v_add_f32_e32 v99, v99, v101
	v_mov_b32_e32 v101, v99
	s_nop 1
	v_permlane16_swap_b32_e32 v99, v101
	v_add_f32_e32 v99, v99, v101
	s_nop 1
	v_add_f32_dpp v99, v99, v99 row_ror:8 row_mask:0xf bank_mask:0xf
	s_nop 1
	v_add_f32_dpp v99, v99, v99 row_half_mirror row_mask:0xf bank_mask:0xf
	s_nop 1
	v_add_f32_dpp v99, v99, v99 quad_perm:[2,3,0,1] row_mask:0xf bank_mask:0xf
	s_nop 1
	v_add_f32_dpp v99, v99, v99 quad_perm:[1,0,3,2] row_mask:0xf bank_mask:0xf
	v_fmamk_f32 v99, v99, 0x3a800000, v146
	v_mul_f32_e32 v101, 0x4b800000, v99
	v_cmp_gt_f32_e32 vcc, s54, v99
	s_nop 1
	v_cndmask_b32_e32 v99, v99, v101, vcc
	v_rsq_f32_e32 v99, v99
	s_nop 0
	v_mul_f32_e32 v101, 0x45800000, v99
	v_cndmask_b32_e32 v208, v99, v101, vcc
	v_pk_mul_f32 v[172:173], v[172:173], v[208:209] op_sel_hi:[1,0]
	v_pk_mul_f32 v[170:171], v[170:171], v[208:209] op_sel_hi:[1,0]
	v_pk_fma_f32 v[172:173], v[2:3], v[172:173], v[10:11]
	v_pk_fma_f32 v[170:171], v[4:5], v[170:171], v[12:13]
	v_cvt_pk_bf16_f32 v212, v172, v173
	v_cvt_pk_bf16_f32 v213, v170, v171
	v_pk_fma_f32 v[172:173], v[168:169], v[172:173], v[34:35]
	v_pk_fma_f32 v[170:171], v[166:167], v[170:171], v[36:37]
	v_cvt_pk_bf16_f32 v172, v172, v173
	v_cvt_pk_bf16_f32 v173, v170, v171
	v_add_co_u32_e32 v170, vcc, s2, v188
	global_store_dwordx2 v[174:175], v[212:213], off nt
	s_nop 0
	v_addc_co_u32_e32 v171, vcc, 0, v189, vcc
	global_store_dwordx2 v[170:171], v[172:173], off
	v_pk_mul_f32 v[172:173], v[186:187], v[208:209] op_sel_hi:[1,0]
	v_pk_mul_f32 v[186:187], v[206:207], v[208:209] op_sel_hi:[1,0]
	v_pk_fma_f32 v[172:173], v[6:7], v[172:173], v[14:15]
	v_pk_fma_f32 v[186:187], v[8:9], v[186:187], v[16:17]
	v_cvt_pk_bf16_f32 v188, v172, v173
	v_cvt_pk_bf16_f32 v189, v186, v187
	v_pk_fma_f32 v[172:173], v[162:163], v[172:173], v[38:39]
	v_pk_fma_f32 v[186:187], v[164:165], v[186:187], v[40:41]
	v_cvt_pk_bf16_f32 v172, v172, v173
	v_cvt_pk_bf16_f32 v173, v186, v187
	global_store_dwordx2 v[174:175], v[188:189], off offset:512 nt
	global_store_dwordx2 v[170:171], v[172:173], off offset:512
	v_pk_mul_f32 v[172:173], v[190:191], v[208:209] op_sel_hi:[1,0]
	v_pk_mul_f32 v[186:187], v[210:211], v[208:209] op_sel_hi:[1,0]
	v_pk_fma_f32 v[172:173], v[18:19], v[172:173], v[26:27]
	v_pk_fma_f32 v[186:187], v[20:21], v[186:187], v[28:29]
	v_cvt_pk_bf16_f32 v188, v172, v173
	v_cvt_pk_bf16_f32 v189, v186, v187
	v_pk_fma_f32 v[172:173], v[160:161], v[172:173], v[70:71]
	v_pk_fma_f32 v[186:187], v[158:159], v[186:187], v[72:73]
	v_cvt_pk_bf16_f32 v172, v172, v173
	v_cvt_pk_bf16_f32 v173, v186, v187
	global_store_dwordx2 v[174:175], v[188:189], off offset:1024 nt
	global_store_dwordx2 v[170:171], v[172:173], off offset:1024
	v_pk_mul_f32 v[172:173], v[184:185], v[208:209] op_sel_hi:[1,0]
	s_nop 0
	v_pk_fma_f32 v[184:185], v[22:23], v[172:173], v[30:31]
	v_pk_mul_f32 v[172:173], v[192:193], v[208:209] op_sel_hi:[1,0]
	s_nop 0
	v_pk_fma_f32 v[186:187], v[24:25], v[172:173], v[32:33]
	v_cvt_pk_bf16_f32 v172, v184, v185
	v_cvt_pk_bf16_f32 v173, v186, v187
	global_store_dwordx2 v[174:175], v[172:173], off offset:1536 nt
	v_pk_add_f32 v[172:173], v[78:79], 1.0 op_sel_hi:[1,0]
	s_nop 0
	v_pk_fma_f32 v[174:175], v[172:173], v[184:185], v[74:75]
	s_nop 0
	v_cvt_pk_bf16_f32 v184, v174, v175
	v_pk_add_f32 v[174:175], v[80:81], 1.0 op_sel_hi:[1,0]
	s_nop 0
	v_pk_fma_f32 v[186:187], v[174:175], v[186:187], v[76:77]
	s_nop 0
	v_cvt_pk_bf16_f32 v185, v186, v187
	global_store_dwordx2 v[170:171], v[184:185], off offset:1536
	v_add_u32_e32 v170, 1, v156
	v_cmp_lt_i32_e32 vcc, v170, v83
	s_and_saveexec_b64 s[10:11], vcc
	s_cbranch_execz .LBB0_557
	v_add_u32_e32 v99, 0xffffe001, v156
	v_lshrrev_b32_e32 v99, 12, v99
	s_movk_i32 s2, 0x1ffe
	v_add_u32_e32 v99, 1, v99
	v_cmp_lt_i32_e32 vcc, s2, v156
	s_nop 1
	v_cndmask_b32_e32 v99, 0, v99, vcc
	v_cmp_ne_u32_e32 vcc, v99, v183
	s_and_saveexec_b64 s[12:13], vcc
	s_cbranch_execz .LBB0_556
	v_mul_hi_u32_u24_e32 v35, 0x1800, v99
	v_mul_u32_u24_e32 v34, 0x1800, v99
	v_lshlrev_b64 v[34:35], 2, v[34:35]
	v_lshl_add_u64 v[58:59], v[94:95], 0, v[34:35]
	v_lshl_add_u64 v[34:35], s[6:7], 0, v[34:35]
	v_lshlrev_b32_e32 v36, 2, v82
	v_mov_b32_e32 v37, v1
	v_lshl_add_u64 v[74:75], v[34:35], 0, v[36:37]
	s_movk_i32 s2, 0x1000
	v_add_co_u32_e32 v60, vcc, s2, v74
	v_mov_b32_e32 v183, v99
	s_nop 0
	v_addc_co_u32_e32 v61, vcc, 0, v75, vcc
	global_load_dwordx4 v[34:37], v[74:75], off
	global_load_dwordx4 v[38:41], v[74:75], off offset:1024
	global_load_dwordx4 v[46:49], v[60:61], off
	global_load_dwordx4 v[50:53], v[60:61], off offset:1024
	global_load_dwordx4 v[42:45], v[58:59], off
	global_load_dwordx4 v[54:57], v[58:59], off offset:1024
	global_load_dwordx4 v[66:69], v[60:61], off offset:2048
	global_load_dwordx4 v[78:81], v[60:61], off offset:3072
	global_load_dwordx4 v[62:65], v[58:59], off offset:2048
	s_nop 0
	global_load_dwordx4 v[58:61], v[58:59], off offset:3072
	s_nop 0
	global_load_dwordx4 v[70:73], v[74:75], off offset:2048
	s_nop 0
	global_load_dwordx4 v[74:77], v[74:75], off offset:3072
	s_waitcnt vmcnt(9)
	v_pk_add_f32 v[168:169], v[46:47], 1.0 op_sel_hi:[1,0]
	v_pk_add_f32 v[166:167], v[48:49], 1.0 op_sel_hi:[1,0]
	s_waitcnt vmcnt(8)
	v_pk_add_f32 v[162:163], v[50:51], 1.0 op_sel_hi:[1,0]
	v_pk_add_f32 v[164:165], v[52:53], 1.0 op_sel_hi:[1,0]
	s_waitcnt vmcnt(5)
	v_pk_add_f32 v[160:161], v[66:67], 1.0 op_sel_hi:[1,0]
	v_pk_add_f32 v[158:159], v[68:69], 1.0 op_sel_hi:[1,0]
	s_waitcnt vmcnt(4)
	v_pk_add_f32 v[172:173], v[78:79], 1.0 op_sel_hi:[1,0]
	v_pk_add_f32 v[174:175], v[80:81], 1.0 op_sel_hi:[1,0]
	s_waitcnt vmcnt(0)
	s_branch .LBB0_556
